# P1 K-loop first load segment: all sixteen fragment reads issued before the pointer arithmetic
# baseline (speedup 1.0000x reference)
.LBB0_107:
	ds_read_b128 v[150:153], v248
	ds_read_b128 v[154:157], v248 offset:1024
	ds_read_b128 v[158:161], v248 offset:2048
	ds_read_b128 v[162:165], v248 offset:3072
	ds_read_b128 v[134:137], v249
	ds_read_b128 v[138:141], v249 offset:1024
	ds_read_b128 v[142:145], v249 offset:2048
	ds_read_b128 v[146:149], v249 offset:3072
	ds_read_b128 v[166:169], v250
	ds_read_b128 v[170:173], v250 offset:1024
	ds_read_b128 v[174:177], v250 offset:2048
	ds_read_b128 v[178:181], v250 offset:3072
	ds_read_b128 v[182:185], v250 offset:4096
	ds_read_b128 v[186:189], v250 offset:5120
	ds_read_b128 v[190:193], v250 offset:6144
	ds_read_b128 v[194:197], v250 offset:7168
	s_add_i32 m0, s61, 0xc000
	s_mov_b64 s[0:1], s[76:77]
	s_add_u32 s76, s0, 0x100
	s_addc_u32 s77, s1, 0
	s_cmp_lg_u32 s45, 12
	s_cselect_b64 s[88:89], -1, 0
	s_and_b64 s[2:3], s[88:89], exec
	s_cselect_b32 s3, s44, s63
	s_cselect_b32 s2, s36, s65
	s_cselect_b32 s85, s77, s4
	s_cselect_b32 s84, s76, s43
	global_load_lds_dwordx4 v214, s[0:1]
	s_add_i32 m0, s61, 0xe000
	s_nop 0
	global_load_lds_dwordx4 v216, s[0:1]
	s_waitcnt vmcnt(8)
	s_waitcnt lgkmcnt(0)
	s_setprio 1
	s_barrier
	v_mfma_f32_16x16x32_bf16 v[102:105], v[150:153], v[166:169], v[102:105]
	v_mfma_f32_16x16x32_bf16 v[70:73], v[158:161], v[166:169], v[70:73]
	v_mfma_f32_16x16x32_bf16 v[114:117], v[150:153], v[174:177], v[114:117]
	v_mfma_f32_16x16x32_bf16 v[82:85], v[158:161], v[174:177], v[82:85]
	v_mfma_f32_16x16x32_bf16 v[110:113], v[150:153], v[182:185], v[110:113]
	v_mfma_f32_16x16x32_bf16 v[78:81], v[158:161], v[182:185], v[78:81]
	v_mfma_f32_16x16x32_bf16 v[106:109], v[150:153], v[190:193], v[106:109]
	v_mfma_f32_16x16x32_bf16 v[74:77], v[158:161], v[190:193], v[74:77]
	v_mfma_f32_16x16x32_bf16 v[102:105], v[154:157], v[170:173], v[102:105]
	v_mfma_f32_16x16x32_bf16 v[70:73], v[162:165], v[170:173], v[70:73]
	v_mfma_f32_16x16x32_bf16 v[114:117], v[154:157], v[178:181], v[114:117]
	v_mfma_f32_16x16x32_bf16 v[82:85], v[162:165], v[178:181], v[82:85]
	v_mfma_f32_16x16x32_bf16 v[110:113], v[154:157], v[186:189], v[110:113]
	v_mfma_f32_16x16x32_bf16 v[78:81], v[162:165], v[186:189], v[78:81]
	v_mfma_f32_16x16x32_bf16 v[106:109], v[154:157], v[194:197], v[106:109]
	v_mfma_f32_16x16x32_bf16 v[74:77], v[162:165], v[194:197], v[74:77]
	v_mfma_f32_16x16x32_bf16 v[130:133], v[134:137], v[166:169], v[130:133]
	v_mfma_f32_16x16x32_bf16 v[98:101], v[142:145], v[166:169], v[98:101]
	v_mfma_f32_16x16x32_bf16 v[126:129], v[134:137], v[174:177], v[126:129]
	v_mfma_f32_16x16x32_bf16 v[94:97], v[142:145], v[174:177], v[94:97]
	v_mfma_f32_16x16x32_bf16 v[122:125], v[134:137], v[182:185], v[122:125]
	v_mfma_f32_16x16x32_bf16 v[90:93], v[142:145], v[182:185], v[90:93]
	v_mfma_f32_16x16x32_bf16 v[118:121], v[134:137], v[190:193], v[118:121]
	v_mfma_f32_16x16x32_bf16 v[86:89], v[142:145], v[190:193], v[86:89]
	v_mfma_f32_16x16x32_bf16 v[130:133], v[138:141], v[170:173], v[130:133]
	v_mfma_f32_16x16x32_bf16 v[98:101], v[146:149], v[170:173], v[98:101]
	v_mfma_f32_16x16x32_bf16 v[126:129], v[138:141], v[178:181], v[126:129]
	v_mfma_f32_16x16x32_bf16 v[94:97], v[146:149], v[178:181], v[94:97]
	v_mfma_f32_16x16x32_bf16 v[122:125], v[138:141], v[186:189], v[122:125]
	v_mfma_f32_16x16x32_bf16 v[90:93], v[146:149], v[186:189], v[90:93]
	v_mfma_f32_16x16x32_bf16 v[118:121], v[138:141], v[194:197], v[118:121]
	v_mfma_f32_16x16x32_bf16 v[86:89], v[146:149], v[194:197], v[86:89]
	s_setprio 0
	s_barrier
	ds_read_b128 v[190:193], v250 offset:16384
	ds_read_b128 v[194:197], v250 offset:17408
	ds_read_b128 v[182:185], v250 offset:18432
	ds_read_b128 v[186:189], v250 offset:19456
	ds_read_b128 v[174:177], v250 offset:20480
	ds_read_b128 v[178:181], v250 offset:21504
	ds_read_b128 v[166:169], v250 offset:22528
	ds_read_b128 v[170:173], v250 offset:23552
	s_mov_b32 m0, s73
	s_add_u32 s0, s2, 0x40000
	global_load_lds_dwordx4 v208, s[2:3]
	s_mov_b32 m0, s75
	s_addc_u32 s1, s3, 0
	global_load_lds_dwordx4 v212, s[2:3]
	s_mov_b32 m0, s92
	s_nop 0
	global_load_lds_dwordx4 v208, s[0:1]
	s_mov_b32 m0, s93
	s_nop 0
	global_load_lds_dwordx4 v212, s[0:1]
	s_mov_b32 m0, s61
	s_nop 0
	global_load_lds_dwordx4 v206, s[84:85]
	s_mov_b32 m0, s94
	s_nop 0
	global_load_lds_dwordx4 v210, s[84:85]
	s_waitcnt vmcnt(8)
